# p2b: relative-position-bias table loads are issued at phase start but scaled and written to LDS only in the neighbourhood-attention preheader, so the phase no longer starts with an exposed load latenc
# speedup vs baseline: 1.0049x; 1.0034x over previous
.LBB0_666:
	s_cmp_le_i32 s78, s0
	s_cselect_b64 s[12:13], -1, 0
	s_and_b64 s[0:1], s[12:13], s[18:19]
	s_andn2_b64 vcc, exec, s[0:1]
	s_cbranch_vccnz .LBB0_728
	v_mov_b32_e32 v193, v233
	s_mov_b32 s24, s2
	v_mov_b32_e32 v152, v232
	s_mov_b32 s25, s71
	s_mov_b32 s5, s3
	s_movk_i32 s0, 0x744
	s_mov_b64 s[14:15], 0
	v_cmp_gt_i32_e32 vcc, s0, v152
	s_and_saveexec_b64 s[16:17], vcc
	s_cbranch_execz .LBB0_680
	s_mul_i32 s26, s4, 0x744
	v_readlane_b32 s54, v254, 16
	v_readlane_b32 s55, v254, 17
	s_lshl_b64 s[0:1], s[26:27], 2
	v_lshlrev_b32_e32 v2, 2, v152
	s_waitcnt vmcnt(0)
	s_add_u32 s38, s54, s0
	s_addc_u32 s39, s55, s1
	v_readlane_b32 s0, v255, 19
	v_add_u32_e32 v3, 0x1000, v2
	v_cmp_gt_u32_e32 vcc, 0x144, v152
	global_load_dword v250, v2, s[38:39]
	global_load_dword v251, v2, s[38:39] offset:2048
	global_load_dword v252, v3, s[38:39]
	s_and_saveexec_b64 s[40:41], vcc
	global_load_dword v253, v3, s[38:39] offset:2048
	s_or_b64 exec, exec, s[40:41]
.LBB0_680:
	s_or_b64 exec, exec, s[16:17]
	v_and_b32_e64 v0, s5, 7
	v_cmp_eq_u32_e64 s[38:39], 0, v0
	s_and_b64 vcc, exec, s[38:39]
	s_mov_b32 s16, s24
	s_waitcnt lgkmcnt(0)
	s_barrier
	s_cbranch_vccz .LBB0_682
	s_ashr_i32 s1, s24, 31
	s_lshr_b32 s1, s1, 29
	s_add_i32 s1, s24, s1
	s_and_b32 s10, s1, -8
	s_ashr_i32 s0, s5, 3
	s_sub_i32 s10, s24, s10
	s_mul_i32 s0, s10, s0
	s_ashr_i32 s1, s1, 3
	s_add_i32 s16, s0, s1

.LBB0_703:
	v_sub_u32_e64 v0, s0, 4 clamp
	v_ashrrev_i32_e32 v57, 3, v152
	v_readfirstlane_b32 s0, v0
	v_sub_u32_e64 v0, v61, 8 clamp
	v_lshrrev_b32_e32 v5, 2, v57
	v_min_u32_e32 v2, 48, v0
	v_and_b32_e32 v3, 7, v152
	v_bfe_u32 v0, v57, 1, 1
	v_and_b32_e32 v5, 6, v5
	v_bitop3_b32 v0, v0, v3, v5 bitop3:0x36
	v_lshl_add_u32 v65, v0, 4, 0
	v_lshlrev_b32_e32 v0, 3, v152
	v_and_b32_e32 v64, 56, v0
	v_lshlrev_b32_e32 v0, 4, v152
	v_and_b32_e32 v0, 0x3f0, v0
	v_lshrrev_b32_e32 v5, 5, v152
	s_and_b64 s[38:39], s[40:41], exec
	v_lshl_add_u64 v[66:67], s[16:17], 0, v[0:1]
	v_bfe_u32 v0, v152, 4, 1
	v_and_b32_e32 v5, 6, v5
	s_cselect_b32 s1, 24, 0xf8
	v_bitop3_b32 v0, v0, v3, v5 bitop3:0x36
	s_min_u32 s66, s0, s1
	v_readlane_b32 s0, v255, 21
	v_lshl_add_u32 v83, v0, 4, 0
	v_lshlrev_b32_e32 v0, 1, v199
	v_add_u32_e32 v88, s82, v150
	v_lshl_add_u32 v4, v193, 2, s0
	s_add_i32 s10, 0, 0x12000
	s_add_i32 s20, s59, -1
	s_and_b32 s83, s25, 4
	v_and_b32_e32 v85, 24, v0
	s_and_b32 s0, s25, -4
	v_add_u32_e32 v0, 16, v2
	v_or_b32_e32 v120, 4, v88
	s_cmp_eq_u32 s0, 4
	v_cmp_ge_i32_e32 vcc, v120, v2
	v_cmp_lt_i32_e64 s[40:41], v120, v0
	s_cselect_b64 s[80:81], -1, 0
	s_and_b64 s[40:41], vcc, s[40:41]
	v_cmp_ge_i32_e32 vcc, v88, v2
	v_cmp_lt_i32_e64 s[42:43], v88, v0
	v_or_b32_e32 v121, 1, v88
	s_and_b64 s[42:43], vcc, s[42:43]
	v_cmp_ge_i32_e32 vcc, v121, v2
	v_cmp_lt_i32_e64 s[44:45], v121, v0
	v_or_b32_e32 v122, 2, v88
	s_and_b64 s[44:45], vcc, s[44:45]
	v_cmp_ge_i32_e32 vcc, v122, v2
	v_cmp_lt_i32_e64 s[46:47], v122, v0
	v_or_b32_e32 v123, 3, v88
	s_and_b64 s[46:47], vcc, s[46:47]
	v_cmp_ge_i32_e32 vcc, v123, v2
	v_cmp_lt_i32_e64 s[48:49], v123, v0
	v_or_b32_e32 v124, 5, v88
	s_and_b64 s[48:49], vcc, s[48:49]
	v_cmp_ge_i32_e32 vcc, v124, v2
	v_cmp_lt_i32_e64 s[50:51], v124, v0
	v_or_b32_e32 v125, 6, v88
	v_or_b32_e32 v126, 7, v88
	v_lshl_add_u32 v60, v3, 4, s10
	v_and_b32_e32 v3, -16, v193
	s_and_b64 s[50:51], vcc, s[50:51]
	v_cmp_ge_i32_e32 vcc, v125, v2
	v_cmp_lt_i32_e64 s[52:53], v125, v0
	v_cmp_lt_i32_e64 s[54:55], v126, v0
	v_mul_u32_u24_e32 v0, 0x410, v199
	s_movk_i32 s35, 0x410
	s_mul_i32 s26, s58, 0xa00
	v_add_u32_e32 v5, 0x200, v152
	v_add_u32_e32 v6, 0x400, v152
	v_add_u32_e32 v7, 0x600, v152
	v_add_u32_e32 v8, 0x800, v152
	v_add_u32_e32 v9, 0xa00, v152
	v_add_u32_e32 v10, 0xc00, v152
	v_add_u32_e32 v11, 0xe00, v152
	s_and_b64 s[52:53], vcc, s[52:53]
	v_cmp_ge_i32_e32 vcc, v126, v2
	v_add3_u32 v127, s10, v3, v0
	v_mov_b32_e32 v2, v1
	v_mov_b32_e32 v3, v1
	v_mad_u64_u32 v[62:63], s[38:39], v57, s35, v[60:61]
	v_ashrrev_i32_e32 v89, 6, v152
	v_ashrrev_i32_e32 v90, 3, v5
	v_ashrrev_i32_e32 v91, 6, v5
	v_ashrrev_i32_e32 v92, 3, v6
	v_ashrrev_i32_e32 v93, 6, v6
	v_ashrrev_i32_e32 v94, 3, v7
	v_ashrrev_i32_e32 v95, 6, v7
	v_ashrrev_i32_e32 v96, 3, v8
	v_ashrrev_i32_e32 v97, 6, v8
	v_ashrrev_i32_e32 v98, 3, v9
	v_ashrrev_i32_e32 v99, 6, v9
	v_ashrrev_i32_e32 v100, 3, v10
	v_ashrrev_i32_e32 v101, 6, v10
	v_ashrrev_i32_e32 v102, 3, v11
	v_ashrrev_i32_e32 v103, 6, v11
	v_lshrrev_b32_e32 v106, 9, v5
	v_lshrrev_b32_e32 v108, 9, v6
	v_lshrrev_b32_e32 v110, 9, v7
	v_lshrrev_b32_e32 v112, 9, v8
	v_lshrrev_b32_e32 v114, 9, v9
	v_lshrrev_b32_e32 v116, 9, v10
	v_lshrrev_b32_e32 v118, 9, v11
	v_mov_b32_e32 v0, v1
	v_add_u32_e32 v128, s26, v4
	v_mov_b64_e32 v[6:7], v[2:3]
	v_mov_b64_e32 v[10:11], v[2:3]
	s_mov_b32 s1, 2
	v_lshrrev_b32_e32 v63, 3, v152
	v_bfe_u32 v82, v152, 3, 6
	s_mov_b32 s38, -1
	v_add_u32_e32 v84, 0x200, v57
	v_and_b32_e32 v86, 3, v193
	v_add_u32_e32 v87, 4, v198
	v_lshrrev_b32_e32 v104, 9, v152
	v_mul_lo_u32 v105, v89, s35
	v_mul_lo_u32 v107, v91, s35
	v_mul_lo_u32 v109, v93, s35
	v_mul_lo_u32 v111, v95, s35
	v_mul_lo_u32 v113, v97, s35
	v_mul_lo_u32 v115, v99, s35
	v_mul_lo_u32 v117, v101, s35
	v_mul_lo_u32 v119, v103, s35
	s_and_b64 s[54:55], vcc, s[54:55]
	v_mov_b32_e32 v129, 0
	v_mov_b32_e32 v130, 0
	v_mov_b32_e32 v131, 0
	v_mov_b32_e32 v132, 0
	v_mov_b32_e32 v133, 0
	v_mov_b32_e32 v134, 0
	v_mov_b32_e32 v135, 0
	v_mov_b32_e32 v136, 0
	v_mov_b32_e32 v137, 0
	v_mov_b32_e32 v138, 0
	v_mov_b32_e32 v139, 0
	v_mov_b32_e32 v140, 0
	v_mov_b32_e32 v141, 0
	v_mov_b32_e32 v142, 0
	v_mov_b32_e32 v143, 0
	v_mov_b32_e32 v144, 0
	v_mov_b32_e32 v145, 0
	v_mov_b32_e32 v146, 0
	v_mov_b32_e32 v147, 0
	v_mov_b32_e32 v148, 0
	v_mov_b32_e32 v149, 0
	v_mov_b32_e32 v152, 0
	v_mov_b32_e32 v154, 0
	v_mov_b32_e32 v155, 0
	v_mov_b32_e32 v156, 0
	v_mov_b32_e32 v157, 0
	v_mov_b32_e32 v158, 0
	v_mov_b32_e32 v159, 0
	v_mov_b32_e32 v160, 0
	v_mov_b32_e32 v161, 0
	v_mov_b32_e32 v162, 0
	v_mov_b32_e32 v163, 0
	v_mov_b64_e32 v[4:5], v[0:1]
	v_mov_b64_e32 v[8:9], v[0:1]
	s_waitcnt vmcnt(0)
	v_readlane_b32 s101, v255, 19
	v_mul_f32_e32 v250, 0x3fb8aa3b, v250
	v_mul_f32_e32 v251, 0x3fb8aa3b, v251
	v_mul_f32_e32 v252, 0x3fb8aa3b, v252
	v_mul_f32_e32 v253, 0x3fb8aa3b, v253
	v_lshl_add_u32 v248, v232, 2, s101
	v_cmp_gt_u32_e32 vcc, 0x144, v232
	ds_write_b32 v248, v250
	ds_write_b32 v248, v251 offset:2048
	ds_write_b32 v248, v252 offset:4096
	s_and_saveexec_b64 s[98:99], vcc
	ds_write_b32 v248, v253 offset:6144
	s_or_b64 exec, exec, s[98:99]
	v_add_u32_e32 v250, s82, v85
	v_or_b32_e32 v251, v250, v86
	v_lshrrev_b32_e32 v250, 2, v250
	v_lshlrev_b32_e32 v252, 7, v251
	v_bfe_u32 v251, v251, 1, 1
	v_and_b32_e32 v250, 6, v250
	v_bitop3_b32 v248, v251, v198, v250 bitop3:0x36
	v_bitop3_b32 v249, v251, v87, v250 bitop3:0x36
	v_lshl_add_u32 v248, v248, 4, v252
	v_lshl_add_u32 v249, v249, 4, v252
	s_mov_b32 s100, 0x3e38aa3b
	v_mov_b32_e32 v224, 0
	v_mov_b32_e32 v225, 0
	s_branch .LBB0_705
